# attention: softmax scale/exp tail and running-max/sum updates moved from between the two barriers into the PV MFMA gaps (both half-steps)
# baseline (speedup 1.0000x reference)
; __device__ __forceinline__ void finishSM(f32x16& p0, f32x16& p1, float alpha, float& l_reg, bf16x8& pa0, bf16x8& pa1, bf16x8& pa2, bf16x8& pa3) {
; #pragma unroll
;     for (int r = 0; r < 16; ++r) p1[r] = __builtin_amdgcn_exp2f(p1[r]);
;     float ps = 0;
; #pragma unroll
;     for (int r = 0; r < 16; ++r) ps += p0[r];
; #pragma unroll
;     for (int r = 0; r < 16; ++r) ps += p1[r];
;     { auto rr = __builtin_amdgcn_permlane32_swap(__float_as_uint(ps), __float_as_uint(ps), false, false);
;       ps = __uint_as_float(rr[0]) + __uint_as_float(rr[1]); }
;     l_reg = l_reg * alpha + ps;
;     ...
;     PK4(p0, 0, pa0); PK4(p0, 8, pa1); PK4(p1, 0, pa2); PK4(p1, 8, pa3);
;     ...
; }
; template <int KB>
; __device__ __forceinline__ void qkt(f32x16& p0, f32x16& p1, const char* K_lds, int r32, int hi, const bf16x8* qr) {
;     p0 = f32x16{}; p1 = f32x16{};
;     const char* kb[4];
; #pragma unroll
;     for (int dd = 0; dd < 4; ++dd) kb[dd] = K_lds + KB * SHM_K + KSWZ(r32, (dd * 16 + hi * 8) * 2);
; #pragma unroll
;     for (int d0 = 0; d0 < 8; ++d0) { const char* a = kb[d0 & 3] + (d0 >> 2) * 128;
;         bf16x8 b0 = *reinterpret_cast<const bf16x8*>(a);
;         bf16x8 b1 = *reinterpret_cast<const bf16x8*>(a + 32 * 256);
;         p0 = __builtin_amdgcn_mfma_f32_32x32x16_bf16(b0, qr[d0], p0, 0, 0, 0);
;         p1 = __builtin_amdgcn_mfma_f32_32x32x16_bf16(b1, qr[d0], p1, 0, 0, 0); }
; }
; template <int VB>
; __device__ __forceinline__ void pv_tile(f32x16* o, int vb0, bf16x8 pa0, bf16x8 pa1, bf16x8 pa2, bf16x8 pa3) {
.LBB0_1299:
	v_add_u32_e32 v146, -8, v179
	global_load_dwordx2 v[146:147], v146, s[68:69]
	v_lshl_add_u64 v[130:131], v[188:189], 0, v[170:171]
	v_lshl_add_u64 v[138:139], v[190:191], 0, v[170:171]
	v_lshl_add_u64 v[134:135], v[130:131], 0, s[100:101]
	v_lshl_add_u64 v[130:131], v[130:131], 0, s[16:17]
	v_lshl_add_u64 v[142:143], v[138:139], 0, s[100:101]
	v_lshl_add_u64 v[138:139], v[138:139], 0, s[16:17]
	global_load_dwordx4 v[130:133], v[130:131], off
	global_load_dwordx4 v[134:137], v[134:135], off
	global_load_dwordx4 v[138:141], v[138:139], off
	global_load_dwordx4 v[142:145], v[142:143], off
	ds_read_b128 v[66:69], v199 offset:49152
	ds_read_b128 v[82:85], v199 offset:57344
	ds_read_b128 v[172:175], v200 offset:49152
	ds_read_b128 v[232:235], v200 offset:57344
	ds_read_b128 v[236:239], v201 offset:49152
	ds_read_b128 v[240:243], v201 offset:57344
	ds_read_b128 v[244:247], v202 offset:49152
	v_exp_f32_e32 v209, v150
	v_add_f32_e32 v150, 0, v219
	v_add_f32_e32 v150, v220, v150
	v_add_f32_e32 v150, v221, v150
	s_waitcnt lgkmcnt(6)
	v_mfma_f32_32x32x16_bf16 v[66:81], v[66:69], v[126:129], 0
	v_add_f32_e32 v150, v222, v150
	v_add_f32_e32 v150, v223, v150
	v_add_f32_e32 v150, v225, v150
	v_add_f32_e32 v150, v224, v150
	v_add_f32_e32 v150, v226, v150
	s_waitcnt lgkmcnt(5)
	v_mfma_f32_32x32x16_bf16 v[82:97], v[82:85], v[126:129], 0
	v_add_f32_e32 v150, v211, v150
	v_add_f32_e32 v150, v212, v150
	v_exp_f32_e32 v194, v194
	s_waitcnt lgkmcnt(4)
	v_mfma_f32_32x32x16_bf16 v[66:81], v[172:175], v[122:125], v[66:81]
	ds_read_b128 v[172:175], v202 offset:57344
	v_exp_f32_e32 v195, v195
	v_exp_f32_e32 v192, v192
	v_exp_f32_e32 v193, v193
	s_waitcnt lgkmcnt(4)
	v_mfma_f32_32x32x16_bf16 v[82:97], v[232:235], v[122:125], v[82:97]
	ds_read_b128 v[232:235], v199 offset:49280
	v_exp_f32_e32 v158, v158
	v_exp_f32_e32 v159, v159
	s_waitcnt lgkmcnt(4)
	v_mfma_f32_32x32x16_bf16 v[66:81], v[236:239], v[118:121], v[66:81]
	ds_read_b128 v[236:239], v199 offset:57472
	v_exp_f32_e32 v207, v154
	v_exp_f32_e32 v208, v155
	v_exp_f32_e32 v210, v151
	s_waitcnt lgkmcnt(4)
	v_mfma_f32_32x32x16_bf16 v[82:97], v[240:243], v[118:121], v[82:97]
	ds_read_b128 v[240:243], v200 offset:49280
	v_exp_f32_e32 v160, v160
	v_exp_f32_e32 v161, v161
	s_waitcnt lgkmcnt(4)
	v_mfma_f32_32x32x16_bf16 v[66:81], v[244:247], v[114:117], v[66:81]
	ds_read_b128 v[244:247], v200 offset:57472
	v_exp_f32_e32 v227, v156
	v_cvt_pk_bf16_f32 v151, v224, v226
	v_cvt_pk_bf16_f32 v154, v214, v216
	v_cvt_pk_bf16_f32 v155, v217, v218
	v_cvt_pk_bf16_f32 v156, v194, v195
	s_waitcnt lgkmcnt(4)
	v_mfma_f32_32x32x16_bf16 v[82:97], v[172:175], v[114:117], v[82:97]
	ds_read_b128 v[172:175], v201 offset:49280
	v_exp_f32_e32 v228, v157
	v_exp_f32_e32 v229, v152
	s_waitcnt lgkmcnt(4)
	v_mfma_f32_32x32x16_bf16 v[66:81], v[232:235], v[110:113], v[66:81]
	ds_read_b128 v[232:235], v201 offset:57472
	v_exp_f32_e32 v230, v153
	v_cvt_pk_bf16_f32 v152, v211, v212
	v_cvt_pk_bf16_f32 v153, v213, v215
	v_cvt_pk_bf16_f32 v157, v192, v193
	v_cvt_pk_bf16_f32 v211, v229, v230
	s_waitcnt lgkmcnt(4)
	v_mfma_f32_32x32x16_bf16 v[82:97], v[236:239], v[110:113], v[82:97]
	ds_read_b128 v[236:239], v202 offset:49280
	v_permlane32_swap_b32_e32 v152, v154
	v_permlane32_swap_b32_e32 v153, v155
	v_add_f32_e32 v249, v213, v150
	v_add_f32_e32 v249, v215, v249
	v_add_f32_e32 v249, v214, v249
	s_waitcnt lgkmcnt(4)
	v_mfma_f32_32x32x16_bf16 v[66:81], v[240:243], v[106:109], v[66:81]
	ds_read_b128 v[240:243], v202 offset:57472
	v_add_f32_e32 v249, v216, v249
	v_add_f32_e32 v249, v217, v249
	v_add_f32_e32 v249, v218, v249
	v_add_f32_e32 v249, v194, v249
	v_add_f32_e32 v248, v195, v249
	s_waitcnt lgkmcnt(4)
	v_mfma_f32_32x32x16_bf16 v[82:97], v[244:247], v[106:109], v[82:97]
	v_add_f32_e32 v248, v192, v248
	v_add_f32_e32 v248, v193, v248
	v_add_f32_e32 v248, v158, v248
	v_add_f32_e32 v248, v159, v248
	v_add_f32_e32 v248, v207, v248
	s_waitcnt lgkmcnt(3)
	v_mfma_f32_32x32x16_bf16 v[66:81], v[172:175], v[102:105], v[66:81]
	v_add_f32_e32 v248, v208, v248
	v_add_f32_e32 v248, v209, v248
	v_add_f32_e32 v248, v210, v248
	v_add_f32_e32 v248, v160, v248
	v_add_f32_e32 v248, v161, v248
	s_waitcnt lgkmcnt(2)
	v_mfma_f32_32x32x16_bf16 v[82:97], v[232:235], v[102:105], v[82:97]
	v_add_f32_e32 v248, v227, v248
	v_add_f32_e32 v248, v228, v248
	v_add_f32_e32 v248, v229, v248
	v_add_f32_e32 v181, v230, v248
	v_mov_b32_e32 v187, v181
	s_waitcnt lgkmcnt(1)
	v_mfma_f32_32x32x16_bf16 v[66:81], v[236:239], v[98:101], v[66:81]
	v_cvt_pk_bf16_f32 v148, v219, v220
	v_cvt_pk_bf16_f32 v149, v221, v222
	v_cvt_pk_bf16_f32 v150, v223, v225
	v_cvt_pk_bf16_f32 v158, v158, v159
	v_cvt_pk_bf16_f32 v159, v207, v208
	s_waitcnt lgkmcnt(0)
	v_mfma_f32_32x32x16_bf16 v[82:97], v[240:243], v[98:101], v[82:97]
	v_cvt_pk_bf16_f32 v208, v209, v210
	v_cvt_pk_bf16_f32 v210, v227, v228
	v_permlane32_swap_b32_e32 v181, v187
	v_permlane32_swap_b32_e32 v148, v150
	v_permlane32_swap_b32_e32 v149, v151
	v_cvt_pk_bf16_f32 v209, v160, v161
	v_permlane32_swap_b32_e32 v208, v210
	v_permlane32_swap_b32_e32 v156, v158
	v_permlane32_swap_b32_e32 v157, v159
	v_permlane32_swap_b32_e32 v209, v211
	v_lshl_add_u64 v[194:195], v[188:189], 0, v[170:171]
	v_lshl_add_u64 v[192:193], v[190:191], 0, v[170:171]
	ds_read_b64_tr_b16 v[172:173], v1 offset:0x0
	ds_read_b64_tr_b16 v[174:175], v1 offset:0x800
	ds_read_b64_tr_b16 v[232:233], v1 offset:0x200
	ds_read_b64_tr_b16 v[234:235], v1 offset:0xa00
	ds_read_b64_tr_b16 v[236:237], v1 offset:0x400
	ds_read_b64_tr_b16 v[238:239], v1 offset:0xc00
	ds_read_b64_tr_b16 v[240:241], v1 offset:0x600
	ds_read_b64_tr_b16 v[242:243], v1 offset:0xe00
	ds_read_b64_tr_b16 v[244:245], v1 offset:0x1000
	ds_read_b64_tr_b16 v[246:247], v1 offset:0x1800
	ds_read_b64_tr_b16 v[248:249], v1 offset:0x1200
	ds_read_b64_tr_b16 v[250:251], v1 offset:0x1a00
	s_nop 0
	s_waitcnt lgkmcnt(10)
; __device__ __forceinline__ void sel_mask_tile(f32x16& p0, f32x16& p1, unsigned wlo, unsigned whi, int hi) {
;     const unsigned NEGB = 0xff800000u;
;     const unsigned lo = wlo >> (4 * hi), h2 = whi >> (4 * hi);
; #pragma unroll
;     for (int r = 0; r < 16; ++r) {
;         const int c = (r & 3) + 8 * (r >> 2);
;         const unsigned m0 = (unsigned)__builtin_amdgcn_sbfe((int)lo, c, 1), m1 = (unsigned)__builtin_amdgcn_sbfe((int)h2, c, 1);
;         p0[r] = __uint_as_float((__float_as_uint(p0[r]) & m0) | (NEGB & ~m0));
;         p1[r] = __uint_as_float((__float_as_uint(p1[r]) & m1) | (NEGB & ~m1));
;     }
; }
; __device__ __forceinline__ void partialSM(f32x16& p0, f32x16& p1, float& m_reg, float& mn, float& alpha) {
;     float pmax = p0[0];
; #pragma unroll
;     for (int r = 1; r < 16; ++r) pmax = fmaxf(pmax, p0[r]);
; #pragma unroll
;     for (int r = 0; r < 16; ++r) pmax = fmaxf(pmax, p1[r]);
;     { auto rr = __builtin_amdgcn_permlane32_swap(__float_as_uint(pmax), __float_as_uint(pmax), false, false);
;       pmax = fmaxf(__uint_as_float(rr[0]), __uint_as_float(rr[1])); }
;     constexpr float C2 = 1.4426950408889634f * SCALE;
;     if (__builtin_expect(__all((pmax - m_reg) * SCALE <= THR), 1)) { mn = m_reg; alpha = 1.f; }
; template <int VB>
; __device__ __forceinline__ void pv_tile(f32x16* o, int vb0, bf16x8 pa0, bf16x8 pa1, bf16x8 pa2, bf16x8 pa3) {
;     ...
;     PV_D0(0); PV_D0(1); PV_D0(2); PV_D0(3);
	v_mfma_f32_32x32x16_bf16 v[2:17], v[148:151], v[172:175], v[2:17]
	ds_read_b64_tr_b16 v[172:173], v1 offset:0x1400
	ds_read_b64_tr_b16 v[174:175], v1 offset:0x1c00
	s_waitcnt vmcnt(4)
	v_lshrrev_b32_e32 v160, v163, v146
	v_lshrrev_b32_e32 v161, v163, v147
	v_bfe_i32 v146, v160, 0, 1
	v_bfe_i32 v147, v161, 0, 1
	v_bitop3_b32 v146, v66, s74, v146 bitop3:0xe4
	v_bitop3_b32 v66, v82, s74, v147 bitop3:0xe4
	v_bfe_i32 v82, v160, 1, 1
	v_bfe_i32 v147, v161, 1, 1
	v_bitop3_b32 v82, v67, s74, v82 bitop3:0xe4
	v_bitop3_b32 v67, v83, s74, v147 bitop3:0xe4
	s_waitcnt lgkmcnt(10)
	v_mfma_f32_32x32x16_bf16 v[50:65], v[148:151], v[232:235], v[50:65]
	ds_read_b64_tr_b16 v[232:233], v1 offset:0x1600
	ds_read_b64_tr_b16 v[234:235], v1 offset:0x1e00
	v_bfe_i32 v83, v160, 2, 1
	v_bfe_i32 v147, v161, 2, 1
	v_bitop3_b32 v83, v68, s74, v83 bitop3:0xe4
	v_bitop3_b32 v68, v84, s74, v147 bitop3:0xe4
	v_bfe_i32 v84, v160, 3, 1
	s_waitcnt lgkmcnt(10)
	v_mfma_f32_32x32x16_bf16 v[34:49], v[148:151], v[236:239], v[34:49]
	ds_read_b64_tr_b16 v[236:237], v1 offset:0x2000
	ds_read_b64_tr_b16 v[238:239], v1 offset:0x2800
	s_waitcnt lgkmcnt(10)
	v_mfma_f32_32x32x16_bf16 v[18:33], v[148:151], v[240:243], v[18:33]
	ds_read_b64_tr_b16 v[240:241], v1 offset:0x2200
	ds_read_b64_tr_b16 v[242:243], v1 offset:0x2a00
	v_bfe_i32 v148, v161, 3, 1
	v_bitop3_b32 v147, v69, s74, v84 bitop3:0xe4
	v_bfe_i32 v84, v160, 8, 1
	v_bitop3_b32 v69, v85, s74, v148 bitop3:0xe4
	v_bfe_i32 v85, v161, 8, 1
	v_bitop3_b32 v148, v70, s74, v84 bitop3:0xe4
	v_bfe_i32 v84, v160, 9, 1
	v_bitop3_b32 v70, v86, s74, v85 bitop3:0xe4
	v_bfe_i32 v85, v161, 9, 1
	v_bitop3_b32 v149, v71, s74, v84 bitop3:0xe4
	v_bfe_i32 v84, v160, 10, 1
	v_bitop3_b32 v71, v87, s74, v85 bitop3:0xe4
	s_waitcnt lgkmcnt(10)
	v_mfma_f32_32x32x16_bf16 v[2:17], v[152:155], v[244:247], v[2:17]
	ds_read_b64_tr_b16 v[244:245], v1 offset:0x2400
	ds_read_b64_tr_b16 v[246:247], v1 offset:0x2c00
	v_bfe_i32 v85, v161, 10, 1
	v_bitop3_b32 v87, v72, s74, v84 bitop3:0xe4
	v_bfe_i32 v84, v160, 11, 1
	v_bitop3_b32 v72, v88, s74, v85 bitop3:0xe4
	v_bfe_i32 v85, v161, 11, 1
	v_bitop3_b32 v88, v73, s74, v84 bitop3:0xe4
	v_bfe_i32 v73, v160, 16, 1
	v_bitop3_b32 v84, v89, s74, v85 bitop3:0xe4
	v_bfe_i32 v85, v161, 16, 1
	v_bitop3_b32 v89, v74, s74, v73 bitop3:0xe4
	v_bfe_i32 v73, v160, 17, 1
	v_bfe_i32 v74, v161, 17, 1
	s_waitcnt lgkmcnt(10)
	v_mfma_f32_32x32x16_bf16 v[50:65], v[152:155], v[248:251], v[50:65]
	ds_read_b64_tr_b16 v[248:249], v1 offset:0x2600
	ds_read_b64_tr_b16 v[250:251], v1 offset:0x2e00
	v_bitop3_b32 v85, v90, s74, v85 bitop3:0xe4
	v_bitop3_b32 v90, v75, s74, v73 bitop3:0xe4
	v_bitop3_b32 v86, v91, s74, v74 bitop3:0xe4
	v_bfe_i32 v73, v160, 18, 1
	v_bfe_i32 v74, v161, 18, 1
	v_bitop3_b32 v91, v76, s74, v73 bitop3:0xe4
	v_bitop3_b32 v76, v92, s74, v74 bitop3:0xe4
	v_bfe_i32 v73, v160, 19, 1
	v_bfe_i32 v74, v161, 19, 1
	v_bitop3_b32 v92, v77, s74, v73 bitop3:0xe4
	v_bitop3_b32 v77, v93, s74, v74 bitop3:0xe4
	v_bfe_i32 v73, v160, 24, 1
	s_waitcnt lgkmcnt(10)
	v_mfma_f32_32x32x16_bf16 v[34:49], v[152:155], v[172:175], v[34:49]
	ds_read_b64_tr_b16 v[172:173], v1 offset:0x3000
	ds_read_b64_tr_b16 v[174:175], v1 offset:0x3800
	v_bfe_i32 v74, v161, 24, 1
	v_bitop3_b32 v93, v78, s74, v73 bitop3:0xe4
	v_bitop3_b32 v78, v94, s74, v74 bitop3:0xe4
	v_bfe_i32 v73, v160, 25, 1
	v_bfe_i32 v74, v161, 25, 1
	v_bitop3_b32 v79, v79, s74, v73 bitop3:0xe4
	v_bitop3_b32 v73, v95, s74, v74 bitop3:0xe4
	v_bfe_i32 v74, v160, 26, 1
	v_bfe_i32 v75, v161, 26, 1
	v_bitop3_b32 v80, v80, s74, v74 bitop3:0xe4
	v_bitop3_b32 v74, v96, s74, v75 bitop3:0xe4
	s_waitcnt lgkmcnt(10)
	v_mfma_f32_32x32x16_bf16 v[18:33], v[152:155], v[232:235], v[18:33]
	ds_read_b64_tr_b16 v[232:233], v1 offset:0x3200
	ds_read_b64_tr_b16 v[234:235], v1 offset:0x3a00
	v_bfe_i32 v75, v160, 27, 1
	v_bfe_i32 v94, v161, 27, 1
	v_bitop3_b32 v81, v81, s74, v75 bitop3:0xe4
	v_bitop3_b32 v75, v97, s74, v94 bitop3:0xe4
	v_max_f32_e32 v94, v82, v82
	v_max_f32_e32 v95, v146, v146
	v_max_f32_e32 v94, v95, v94
	v_max3_f32 v94, v94, v83, v147
	v_max3_f32 v94, v94, v148, v149
	v_max3_f32 v94, v94, v87, v88
	v_max3_f32 v94, v94, v89, v90
	v_max3_f32 v94, v94, v91, v92
	s_waitcnt lgkmcnt(10)
	v_mfma_f32_32x32x16_bf16 v[2:17], v[156:159], v[236:239], v[2:17]
	ds_read_b64_tr_b16 v[236:237], v1 offset:0x3400
	ds_read_b64_tr_b16 v[238:239], v1 offset:0x3c00
	v_max3_f32 v94, v94, v93, v79
	v_max3_f32 v94, v94, v80, v81
	v_max3_f32 v94, v94, v66, v67
	v_max3_f32 v94, v94, v68, v69
	v_max3_f32 v94, v94, v70, v71
	v_max3_f32 v94, v94, v72, v84
	v_max3_f32 v94, v94, v85, v86
	v_max3_f32 v94, v94, v76, v77
	v_max3_f32 v94, v94, v78, v73
	v_max3_f32 v94, v94, v74, v75
	v_mov_b32_e32 v95, v94
	s_nop 1
	s_waitcnt lgkmcnt(10)
	v_mfma_f32_32x32x16_bf16 v[50:65], v[156:159], v[240:243], v[50:65]
	ds_read_b64_tr_b16 v[240:241], v1 offset:0x3600
	ds_read_b64_tr_b16 v[242:243], v1 offset:0x3e00
	v_permlane32_swap_b32_e32 v94, v95
	v_max_f32_e32 v95, v95, v95
	v_max_f32_e32 v94, v94, v94
	v_max_f32_e32 v94, v94, v95
	v_max_f32_e32 v96, v206, v206
	v_sub_f32_e32 v95, v94, v206
	v_max_f32_e32 v94, v96, v94
	v_sub_f32_e32 v96, v206, v94
	v_mul_f32_e32 v96, 0x3e0293ee, v96
	v_mul_f32_e32 v95, 0x3db504f3, v95
	s_waitcnt lgkmcnt(10)
; __device__ __forceinline__ void partialSM(f32x16& p0, f32x16& p1, float& m_reg, float& mn, float& alpha) {
;     ...
;     if (__builtin_expect(__all((pmax - m_reg) * SCALE <= THR), 1)) { mn = m_reg; alpha = 1.f; }
;     else { mn = fmaxf(m_reg, pmax); alpha = __builtin_amdgcn_exp2f((m_reg - mn) * C2); m_reg = mn; }
;     const float mnL = -mn * C2;
; #pragma unroll
;     for (int r = 0; r < 16; ++r) p0[r] = fmaf(p0[r], C2, mnL);
; #pragma unroll
;     for (int r = 0; r < 16; ++r) p1[r] = fmaf(p1[r], C2, mnL);
; #pragma unroll
;     for (int r = 0; r < 16; ++r) p0[r] = __builtin_amdgcn_exp2f(p0[r]);
	v_mfma_f32_32x32x16_bf16 v[34:49], v[156:159], v[244:247], v[34:49]
	v_exp_f32_e32 v96, v96
	v_cmp_ge_f32_e32 vcc, s75, v95
	s_cmp_eq_u64 vcc, exec
	s_cselect_b64 s[6:7], -1, 0
	v_cndmask_b32_e64 v206, v94, v206, s[6:7]
	v_mul_f32_e32 v207, 0xbe0293ee, v206
	v_fmamk_f32 v146, v146, 0x3e0293ee, v207
	v_exp_f32_e32 v146, v146
	v_fmamk_f32 v217, v66, 0x3e0293ee, v207
	v_fmamk_f32 v218, v67, 0x3e0293ee, v207
	v_fmamk_f32 v219, v68, 0x3e0293ee, v207
	s_waitcnt lgkmcnt(8)
	v_mfma_f32_32x32x16_bf16 v[18:33], v[156:159], v[248:251], v[18:33]
	v_fmamk_f32 v220, v69, 0x3e0293ee, v207
	v_fmamk_f32 v221, v70, 0x3e0293ee, v207
	v_fmamk_f32 v212, v84, 0x3e0293ee, v207
	v_fmamk_f32 v213, v85, 0x3e0293ee, v207
	v_fmamk_f32 v214, v86, 0x3e0293ee, v207
	v_fmamk_f32 v215, v76, 0x3e0293ee, v207
	v_fmamk_f32 v216, v77, 0x3e0293ee, v207
	v_fmamk_f32 v222, v73, 0x3e0293ee, v207
	v_fmamk_f32 v223, v74, 0x3e0293ee, v207
	v_fmamk_f32 v160, v148, 0x3e0293ee, v207
	v_exp_f32_e32 v160, v160
	s_waitcnt lgkmcnt(6)
	v_mfma_f32_32x32x16_bf16 v[2:17], v[208:211], v[172:175], v[2:17]
	v_fmamk_f32 v148, v83, 0x3e0293ee, v207
	v_fmamk_f32 v161, v149, 0x3e0293ee, v207
	v_exp_f32_e32 v161, v161
	v_fmamk_f32 v149, v87, 0x3e0293ee, v207
	v_fmamk_f32 v150, v89, 0x3e0293ee, v207
	v_fmamk_f32 v151, v90, 0x3e0293ee, v207
	v_exp_f32_e32 v148, v148
	v_exp_f32_e32 v149, v149
	s_waitcnt lgkmcnt(4)
	v_mfma_f32_32x32x16_bf16 v[50:65], v[208:211], v[232:235], v[50:65]
	v_exp_f32_e32 v150, v150
	v_exp_f32_e32 v151, v151
	v_fmamk_f32 v155, v91, 0x3e0293ee, v207
	v_fmamk_f32 v152, v93, 0x3e0293ee, v207
	v_fmamk_f32 v153, v79, 0x3e0293ee, v207
	v_fmamk_f32 v154, v80, 0x3e0293ee, v207
	v_exp_f32_e32 v155, v155
	v_exp_f32_e32 v152, v152
	s_waitcnt lgkmcnt(2)
	v_mfma_f32_32x32x16_bf16 v[34:49], v[208:211], v[236:239], v[34:49]
	v_exp_f32_e32 v153, v153
	v_exp_f32_e32 v154, v154
	v_fmamk_f32 v159, v147, 0x3e0293ee, v207
	v_fmamk_f32 v147, v82, 0x3e0293ee, v207
	v_exp_f32_e32 v147, v147
	v_fmamk_f32 v158, v88, 0x3e0293ee, v207
	v_fmamk_f32 v157, v92, 0x3e0293ee, v207
	v_fmamk_f32 v156, v81, 0x3e0293ee, v207
	s_waitcnt lgkmcnt(0)
	v_mfma_f32_32x32x16_bf16 v[18:33], v[208:211], v[240:243], v[18:33]
	s_waitcnt vmcnt(0)
	ds_write_b128 v204, v[138:141] offset:32768
	ds_write_b128 v204, v[142:145] offset:40960
	v_exp_f32_e32 v159, v159
	v_exp_f32_e32 v158, v158
	v_exp_f32_e32 v157, v157
	v_exp_f32_e32 v156, v156
	v_fmamk_f32 v210, v71, 0x3e0293ee, v207
	v_fmamk_f32 v209, v78, 0x3e0293ee, v207
	v_fmamk_f32 v211, v72, 0x3e0293ee, v207
	v_fmac_f32_e32 v207, 0x3e0293ee, v75
	s_barrier
	s_waitcnt vmcnt(0)
	v_cndmask_b32_e64 v208, v96, 1.0, s[6:7]
	v_cmp_gt_f32_e32 vcc, 1.0, v208
	ds_write_b128 v197, v[130:133]
	ds_write_b128 v198, v[134:137]
	s_cbranch_vccz .LBB0_1303
	s_and_saveexec_b64 s[36:37], s[0:1]
	ds_write_b32 v185, v208 offset:128
	s_or_b64 exec, exec, s[36:37]
	s_waitcnt lgkmcnt(0)
	ds_read_b128 v[232:235], v183 offset:224
	ds_read_b128 v[236:239], v183 offset:192
	ds_read_b128 v[240:243], v183 offset:160
	ds_read_b128 v[172:175], v183 offset:128
	s_waitcnt lgkmcnt(3)
	v_pk_mul_f32 v[16:17], v[16:17], v[234:235]
	s_waitcnt lgkmcnt(2)
	v_pk_mul_f32 v[12:13], v[12:13], v[238:239]
	s_waitcnt lgkmcnt(1)
	v_pk_mul_f32 v[8:9], v[8:9], v[242:243]
	s_waitcnt lgkmcnt(0)
	v_pk_mul_f32 v[4:5], v[4:5], v[174:175]
	v_pk_mul_f32 v[14:15], v[14:15], v[232:233]
	v_pk_mul_f32 v[10:11], v[10:11], v[236:237]
	v_pk_mul_f32 v[6:7], v[6:7], v[240:241]
	v_pk_mul_f32 v[2:3], v[2:3], v[172:173]
	v_pk_mul_f32 v[64:65], v[64:65], v[234:235]
	v_pk_mul_f32 v[60:61], v[60:61], v[238:239]
	v_pk_mul_f32 v[56:57], v[56:57], v[242:243]
	v_pk_mul_f32 v[52:53], v[52:53], v[174:175]
	v_pk_mul_f32 v[62:63], v[62:63], v[232:233]
	v_pk_mul_f32 v[58:59], v[58:59], v[236:237]
	v_pk_mul_f32 v[54:55], v[54:55], v[240:241]
	v_pk_mul_f32 v[50:51], v[50:51], v[172:173]
	v_pk_mul_f32 v[48:49], v[48:49], v[234:235]
	v_pk_mul_f32 v[44:45], v[44:45], v[238:239]
	v_pk_mul_f32 v[40:41], v[40:41], v[242:243]
	v_pk_mul_f32 v[36:37], v[36:37], v[174:175]
	v_pk_mul_f32 v[46:47], v[46:47], v[232:233]
	v_pk_mul_f32 v[42:43], v[42:43], v[236:237]
	v_pk_mul_f32 v[38:39], v[38:39], v[240:241]
	v_pk_mul_f32 v[34:35], v[34:35], v[172:173]
	v_pk_mul_f32 v[32:33], v[32:33], v[234:235]
	v_pk_mul_f32 v[28:29], v[28:29], v[238:239]
	v_pk_mul_f32 v[24:25], v[24:25], v[242:243]
	v_pk_mul_f32 v[20:21], v[20:21], v[174:175]
	v_pk_mul_f32 v[30:31], v[30:31], v[232:233]
	v_pk_mul_f32 v[26:27], v[26:27], v[236:237]
	v_pk_mul_f32 v[22:23], v[22:23], v[240:241]
	v_pk_mul_f32 v[18:19], v[18:19], v[172:173]
.LBB0_1303:
	s_waitcnt lgkmcnt(0)
	s_barrier
	global_load_dwordx2 v[228:229], v179, s[68:69]
	s_add_i32 s98, s82, 2
	s_cmp_gt_u32 s98, s81
	s_cbranch_scc1 .Lp5_a2
	v_add_co_u32_e32 v130, vcc, 0x60000, v194
	s_nop 1
	v_addc_co_u32_e32 v131, vcc, 0, v195, vcc
	v_add_co_u32_e32 v134, vcc, 0x70000, v194
	s_nop 1
	v_addc_co_u32_e32 v135, vcc, 0, v195, vcc
	v_add_co_u32_e32 v138, vcc, 0x60000, v192
	global_load_dwordx4 v[130:133], v[130:131], off
	s_nop 0
	global_load_dwordx4 v[134:137], v[134:135], off
	v_addc_co_u32_e32 v139, vcc, 0, v193, vcc
	v_add_co_u32_e32 v142, vcc, 0x70000, v192
	s_nop 1
	v_addc_co_u32_e32 v143, vcc, 0, v193, vcc
	global_load_dwordx4 v[138:141], v[138:139], off
	s_nop 0
	global_load_dwordx4 v[142:145], v[142:143], off

; __device__ __forceinline__ void sel_mask_tile(f32x16& p0, f32x16& p1, unsigned wlo, unsigned whi, int hi) {
;     const unsigned NEGB = 0xff800000u;
;     const unsigned lo = wlo >> (4 * hi), h2 = whi >> (4 * hi);
; #pragma unroll
;     for (int r = 0; r < 16; ++r) {
;         const int c = (r & 3) + 8 * (r >> 2);
;         const unsigned m0 = (unsigned)__builtin_amdgcn_sbfe((int)lo, c, 1), m1 = (unsigned)__builtin_amdgcn_sbfe((int)h2, c, 1);
;         p0[r] = __uint_as_float((__float_as_uint(p0[r]) & m0) | (NEGB & ~m0));
;         p1[r] = __uint_as_float((__float_as_uint(p1[r]) & m1) | (NEGB & ~m1));
;     }
; }
; __device__ __forceinline__ void partialSM(f32x16& p0, f32x16& p1, float& m_reg, float& mn, float& alpha) {
;     float pmax = p0[0];
; #pragma unroll
;     for (int r = 1; r < 16; ++r) pmax = fmaxf(pmax, p0[r]);
; #pragma unroll
;     for (int r = 0; r < 16; ++r) pmax = fmaxf(pmax, p1[r]);
;     { auto rr = __builtin_amdgcn_permlane32_swap(__float_as_uint(pmax), __float_as_uint(pmax), false, false);
;       pmax = fmaxf(__uint_as_float(rr[0]), __uint_as_float(rr[1])); }
;     constexpr float C2 = 1.4426950408889634f * SCALE;
;     if (__builtin_expect(__all((pmax - m_reg) * SCALE <= THR), 1)) { mn = m_reg; alpha = 1.f; }
; template <int VB>
; __device__ __forceinline__ void pv_tile(f32x16* o, int vb0, bf16x8 pa0, bf16x8 pa1, bf16x8 pa2, bf16x8 pa3) {
;     ...
;     PV_D0(0); PV_D0(1); PV_D0(2); PV_D0(3);
.LBB0_1305:
	ds_read_b64_tr_b16 v[232:233], v1 offset:0x4000
	ds_read_b64_tr_b16 v[234:235], v1 offset:0x4800
	ds_read_b64_tr_b16 v[236:237], v1 offset:0x4200
	ds_read_b64_tr_b16 v[238:239], v1 offset:0x4a00
	ds_read_b64_tr_b16 v[240:241], v1 offset:0x4400
	ds_read_b64_tr_b16 v[242:243], v1 offset:0x4c00
	ds_read_b64_tr_b16 v[244:245], v1 offset:0x4600
	ds_read_b64_tr_b16 v[246:247], v1 offset:0x4e00
	ds_read_b64_tr_b16 v[248:249], v1 offset:0x5000
	ds_read_b64_tr_b16 v[250:251], v1 offset:0x5800
	s_nop 0
	s_waitcnt lgkmcnt(8)
	v_mfma_f32_32x32x16_bf16 v[2:17], v[146:149], v[232:235], v[2:17]
	ds_read_b64_tr_b16 v[232:233], v1 offset:0x5200
	ds_read_b64_tr_b16 v[234:235], v1 offset:0x5a00
	s_waitcnt vmcnt(4)
	v_lshrrev_b32_e32 v193, v163, v228
	v_bfe_i32 v192, v193, 0, 1
	v_bitop3_b32 v192, v82, s74, v192 bitop3:0xe4
	v_bfe_i32 v82, v193, 1, 1
	s_waitcnt lgkmcnt(8)
	v_mfma_f32_32x32x16_bf16 v[50:65], v[146:149], v[236:239], v[50:65]
	ds_read_b64_tr_b16 v[236:237], v1 offset:0x5400
	ds_read_b64_tr_b16 v[238:239], v1 offset:0x5c00
	s_waitcnt lgkmcnt(8)
	v_mfma_f32_32x32x16_bf16 v[34:49], v[146:149], v[240:243], v[34:49]
	ds_read_b64_tr_b16 v[240:241], v1 offset:0x5600
	ds_read_b64_tr_b16 v[242:243], v1 offset:0x5e00
	s_waitcnt lgkmcnt(8)
	v_mfma_f32_32x32x16_bf16 v[18:33], v[146:149], v[244:247], v[18:33]
	ds_read_b64_tr_b16 v[244:245], v1 offset:0x6000
	ds_read_b64_tr_b16 v[246:247], v1 offset:0x6800
	v_bitop3_b32 v146, v83, s74, v82 bitop3:0xe4
	v_bfe_i32 v82, v193, 2, 1
	v_bitop3_b32 v147, v84, s74, v82 bitop3:0xe4
	v_bfe_i32 v82, v193, 3, 1
	v_bitop3_b32 v148, v85, s74, v82 bitop3:0xe4
	v_bfe_i32 v82, v193, 8, 1
	v_bitop3_b32 v149, v86, s74, v82 bitop3:0xe4
	v_bfe_i32 v82, v193, 9, 1
	v_bitop3_b32 v173, v87, s74, v82 bitop3:0xe4
	v_bfe_i32 v82, v193, 10, 1
	v_bitop3_b32 v88, v88, s74, v82 bitop3:0xe4
	v_bfe_i32 v82, v193, 11, 1
	v_bitop3_b32 v89, v89, s74, v82 bitop3:0xe4
	s_waitcnt lgkmcnt(8)
	v_mfma_f32_32x32x16_bf16 v[2:17], v[150:153], v[248:251], v[2:17]
	ds_read_b64_tr_b16 v[248:249], v1 offset:0x6200
	ds_read_b64_tr_b16 v[250:251], v1 offset:0x6a00
	v_bfe_i32 v82, v193, 16, 1
	v_bitop3_b32 v90, v90, s74, v82 bitop3:0xe4
	v_bfe_i32 v82, v193, 17, 1
	v_bitop3_b32 v91, v91, s74, v82 bitop3:0xe4
	v_bfe_i32 v82, v193, 18, 1
	v_bitop3_b32 v92, v92, s74, v82 bitop3:0xe4
	v_bfe_i32 v82, v193, 19, 1
	v_bitop3_b32 v93, v93, s74, v82 bitop3:0xe4
	v_bfe_i32 v82, v193, 24, 1
	v_bitop3_b32 v94, v94, s74, v82 bitop3:0xe4
	v_bfe_i32 v82, v193, 25, 1
	v_bitop3_b32 v95, v95, s74, v82 bitop3:0xe4
	v_bfe_i32 v82, v193, 26, 1
	s_waitcnt lgkmcnt(8)
	v_mfma_f32_32x32x16_bf16 v[50:65], v[150:153], v[232:235], v[50:65]
	ds_read_b64_tr_b16 v[232:233], v1 offset:0x6400
	ds_read_b64_tr_b16 v[234:235], v1 offset:0x6c00
	v_bitop3_b32 v96, v96, s74, v82 bitop3:0xe4
	v_bfe_i32 v82, v193, 27, 1
	v_bitop3_b32 v97, v97, s74, v82 bitop3:0xe4
	v_max_f32_e32 v82, v146, v146
	v_max_f32_e32 v230, v192, v192
	v_max_f32_e32 v82, v230, v82
	v_max3_f32 v82, v82, v147, v148
	v_max3_f32 v82, v82, v149, v173
	v_max3_f32 v82, v82, v88, v89
	v_max3_f32 v82, v82, v90, v91
	v_lshrrev_b32_e32 v194, v163, v229
	v_max3_f32 v82, v82, v92, v93
	v_bfe_i32 v195, v194, 0, 1
	s_waitcnt lgkmcnt(8)
	v_mfma_f32_32x32x16_bf16 v[34:49], v[150:153], v[236:239], v[34:49]
	ds_read_b64_tr_b16 v[236:237], v1 offset:0x6600
	ds_read_b64_tr_b16 v[238:239], v1 offset:0x6e00
	v_bfe_i32 v172, v194, 1, 1
	v_max3_f32 v82, v82, v94, v95
	v_bitop3_b32 v66, v66, s74, v195 bitop3:0xe4
	v_bfe_i32 v83, v194, 2, 1
	v_bfe_i32 v84, v194, 3, 1
	v_max3_f32 v230, v82, v96, v97
	v_bitop3_b32 v67, v67, s74, v172 bitop3:0xe4
	v_bfe_i32 v85, v194, 8, 1
	v_bfe_i32 v86, v194, 9, 1
	v_bitop3_b32 v82, v68, s74, v83 bitop3:0xe4
	v_max3_f32 v68, v230, v66, v67
	v_bitop3_b32 v83, v69, s74, v84 bitop3:0xe4
	s_waitcnt lgkmcnt(8)
	v_mfma_f32_32x32x16_bf16 v[18:33], v[150:153], v[240:243], v[18:33]
	ds_read_b64_tr_b16 v[240:241], v1 offset:0x7000
	ds_read_b64_tr_b16 v[242:243], v1 offset:0x7800
	v_bfe_i32 v87, v194, 10, 1
	v_bfe_i32 v230, v194, 11, 1
	v_bitop3_b32 v84, v70, s74, v85 bitop3:0xe4
	v_max3_f32 v68, v68, v82, v83
	v_bitop3_b32 v85, v71, s74, v86 bitop3:0xe4
	v_bfe_i32 v231, v194, 16, 1
	v_bfe_i32 v174, v194, 17, 1
	v_bitop3_b32 v86, v72, s74, v87 bitop3:0xe4
	v_max3_f32 v68, v68, v84, v85
	v_bitop3_b32 v87, v73, s74, v230 bitop3:0xe4
	v_bfe_i32 v230, v194, 18, 1
	v_bfe_i32 v175, v194, 19, 1
	v_bitop3_b32 v74, v74, s74, v231 bitop3:0xe4
	s_waitcnt lgkmcnt(8)
	v_mfma_f32_32x32x16_bf16 v[2:17], v[154:157], v[244:247], v[2:17]
	ds_read_b64_tr_b16 v[244:245], v1 offset:0x7200
	ds_read_b64_tr_b16 v[246:247], v1 offset:0x7a00
	v_max3_f32 v69, v68, v86, v87
	v_bitop3_b32 v75, v75, s74, v174 bitop3:0xe4
	v_bfe_i32 v231, v194, 24, 1
	v_bfe_i32 v174, v194, 25, 1
	v_bitop3_b32 v68, v76, s74, v230 bitop3:0xe4
	v_max3_f32 v71, v69, v74, v75
	v_bitop3_b32 v69, v77, s74, v175 bitop3:0xe4
	v_bfe_i32 v230, v194, 26, 1
	v_bfe_i32 v175, v194, 27, 1
	v_bitop3_b32 v70, v78, s74, v231 bitop3:0xe4
	v_max3_f32 v73, v71, v68, v69
	v_bitop3_b32 v71, v79, s74, v174 bitop3:0xe4
	s_waitcnt lgkmcnt(8)
	v_mfma_f32_32x32x16_bf16 v[50:65], v[154:157], v[248:251], v[50:65]
	ds_read_b64_tr_b16 v[248:249], v1 offset:0x7400
	ds_read_b64_tr_b16 v[250:251], v1 offset:0x7c00
	v_bitop3_b32 v72, v80, s74, v230 bitop3:0xe4
	v_max3_f32 v76, v73, v70, v71
	v_bitop3_b32 v73, v81, s74, v175 bitop3:0xe4
	v_max3_f32 v76, v76, v72, v73
	v_mov_b32_e32 v77, v76
	s_nop 1
	v_permlane32_swap_b32_e32 v76, v77
	v_max_f32_e32 v77, v77, v77
	v_max_f32_e32 v76, v76, v76
	v_max_f32_e32 v76, v76, v77
	v_sub_f32_e32 v77, v76, v206
	v_mul_f32_e32 v77, 0x3db504f3, v77
	v_cmp_ge_f32_e32 vcc, s75, v77
	s_cmp_eq_u64 vcc, exec
	s_waitcnt lgkmcnt(8)
; __device__ __forceinline__ void partialSM(f32x16& p0, f32x16& p1, float& m_reg, float& mn, float& alpha) {
;     ...
;     if (__builtin_expect(__all((pmax - m_reg) * SCALE <= THR), 1)) { mn = m_reg; alpha = 1.f; }
;     else { mn = fmaxf(m_reg, pmax); alpha = __builtin_amdgcn_exp2f((m_reg - mn) * C2); m_reg = mn; }
;     const float mnL = -mn * C2;
; #pragma unroll
;     for (int r = 0; r < 16; ++r) p0[r] = fmaf(p0[r], C2, mnL);
; #pragma unroll
;     for (int r = 0; r < 16; ++r) p1[r] = fmaf(p1[r], C2, mnL);
; #pragma unroll
;     for (int r = 0; r < 16; ++r) p0[r] = __builtin_amdgcn_exp2f(p0[r]);
; __device__ __forceinline__ void attn_block(const BlockRef& cur, const BlockRef& nxt, char* lds, Seam& S) {
;     ...
;     for (int t = 1; t + 1 < NT; t += 2) {
;         HALF_STEP(pB0, pB1, mnB, alB, pA0, pA1, alA, t, 1, 0, 0);
;         HALF_STEP(pA0, pA1, mnA, alA, pB0, pB1, alB, t + 1, 0, 1, 1);
;     }
	v_mfma_f32_32x32x16_bf16 v[34:49], v[154:157], v[232:235], v[34:49]
	ds_read_b64_tr_b16 v[232:233], v1 offset:0x7600
	ds_read_b64_tr_b16 v[234:235], v1 offset:0x7e00
	s_cselect_b64 s[6:7], -1, 0
	v_max_f32_e32 v77, v206, v206
	v_max_f32_e32 v76, v77, v76
	v_sub_f32_e32 v77, v206, v76
	v_mul_f32_e32 v77, 0x3e0293ee, v77
	v_exp_f32_e32 v77, v77
	s_nop 0
	v_cndmask_b32_e64 v207, v77, 1.0, s[6:7]
	v_cndmask_b32_e64 v206, v76, v206, s[6:7]
	v_mul_f32_e32 v76, 0xbe0293ee, v206
	v_mov_b32_e32 v218, v76
	v_fmamk_f32 v219, v192, 0x3e0293ee, v76
	s_waitcnt lgkmcnt(8)
	v_mfma_f32_32x32x16_bf16 v[18:33], v[154:157], v[236:239], v[18:33]
	v_fmamk_f32 v225, v173, 0x3e0293ee, v76
	v_fmamk_f32 v224, v88, 0x3e0293ee, v76
	v_fmamk_f32 v226, v89, 0x3e0293ee, v76
	v_fmamk_f32 v211, v90, 0x3e0293ee, v76
	v_fmamk_f32 v212, v91, 0x3e0293ee, v76
	v_fmamk_f32 v213, v92, 0x3e0293ee, v76
	v_fmamk_f32 v215, v93, 0x3e0293ee, v76
	v_fmamk_f32 v214, v94, 0x3e0293ee, v76
	v_fmamk_f32 v216, v95, 0x3e0293ee, v76
	v_fmamk_f32 v217, v96, 0x3e0293ee, v76
	v_fmac_f32_e32 v218, 0x3e0293ee, v97
	v_exp_f32_e32 v219, v219
	s_waitcnt lgkmcnt(6)
	v_mfma_f32_32x32x16_bf16 v[2:17], v[158:161], v[240:243], v[2:17]
	v_exp_f32_e32 v225, v225
	v_exp_f32_e32 v224, v224
	v_exp_f32_e32 v226, v226
	v_exp_f32_e32 v211, v211
	v_exp_f32_e32 v212, v212
	v_exp_f32_e32 v213, v213
	s_waitcnt lgkmcnt(4)
	v_mfma_f32_32x32x16_bf16 v[50:65], v[158:161], v[244:247], v[50:65]
	v_exp_f32_e32 v215, v215
	v_exp_f32_e32 v214, v214
	v_exp_f32_e32 v216, v216
	v_exp_f32_e32 v217, v217
	v_exp_f32_e32 v218, v218
	v_pk_fma_f32 v[194:195], v[66:67], s[14:15], v[76:77] op_sel_hi:[1,0,0]
	v_add_f32_e32 v66, v181, v187
	v_fmac_f32_e32 v66, v177, v205
	s_waitcnt lgkmcnt(2)
	v_mfma_f32_32x32x16_bf16 v[34:49], v[158:161], v[248:251], v[34:49]
	v_add_f32_e32 v205, v209, v210
	v_pk_fma_f32 v[192:193], v[82:83], s[14:15], v[76:77] op_sel_hi:[1,0,0]
	v_fmac_f32_e32 v205, v66, v208
	v_add_u32_e32 v179, 16, v179
	v_lshl_add_u64 v[188:189], v[188:189], 0, s[16:17]
	v_lshl_add_u64 v[190:191], v[190:191], 0, s[16:17]
	v_fmamk_f32 v220, v146, 0x3e0293ee, v76
	v_exp_f32_e32 v220, v220
	v_fmamk_f32 v221, v147, 0x3e0293ee, v76
	v_exp_f32_e32 v221, v221
	s_waitcnt lgkmcnt(0)
	v_mfma_f32_32x32x16_bf16 v[18:33], v[158:161], v[232:235], v[18:33]
	s_cmp_eq_u64 s[36:37], 0
	s_cbranch_scc1 .Lp5_kw2_skip
	s_waitcnt vmcnt(0)
	ds_write_b128 v204, v[138:141] offset:49152
	ds_write_b128 v204, v[142:145] offset:57344
.Lp5_kw2_skip:
	v_fmamk_f32 v222, v148, 0x3e0293ee, v76
	v_exp_f32_e32 v222, v222
	v_fmamk_f32 v223, v149, 0x3e0293ee, v76
	v_exp_f32_e32 v223, v223
	v_pk_fma_f32 v[150:151], v[74:75], s[14:15], v[76:77] op_sel_hi:[1,0,0]
	v_pk_fma_f32 v[152:153], v[72:73], s[14:15], v[76:77] op_sel_hi:[1,0,0]
	v_pk_fma_f32 v[154:155], v[86:87], s[14:15], v[76:77] op_sel_hi:[1,0,0]
	v_pk_fma_f32 v[156:157], v[70:71], s[14:15], v[76:77] op_sel_hi:[1,0,0]
	v_pk_fma_f32 v[158:159], v[84:85], s[14:15], v[76:77] op_sel_hi:[1,0,0]
	v_pk_fma_f32 v[160:161], v[68:69], s[14:15], v[76:77] op_sel_hi:[1,0,0]
	s_andn2_b64 vcc, exec, s[36:37]
	s_barrier
	s_cbranch_vccnz .LBB0_1307
	s_waitcnt vmcnt(0)
	ds_write_b128 v197, v[130:133] offset:16384
	ds_write_b128 v198, v[134:137] offset:16384
.LBB0_1307:
	v_cmp_gt_f32_e32 vcc, 1.0, v207
	s_cbranch_vccz .LBB0_1311
	s_and_saveexec_b64 s[36:37], s[0:1]
	ds_write_b32 v185, v207 offset:128
	s_or_b64 exec, exec, s[36:37]
	s_waitcnt lgkmcnt(0)
	ds_read_b128 v[78:81], v183 offset:224
	ds_read_b128 v[130:133], v183 offset:192
	ds_read_b128 v[134:137], v183 offset:160
	ds_read_b128 v[138:141], v183 offset:128
	s_waitcnt lgkmcnt(3)
	v_pk_mul_f32 v[16:17], v[16:17], v[80:81]
	s_waitcnt lgkmcnt(2)
	v_pk_mul_f32 v[12:13], v[12:13], v[132:133]
	s_waitcnt lgkmcnt(1)
	v_pk_mul_f32 v[8:9], v[8:9], v[136:137]
	s_waitcnt lgkmcnt(0)
	v_pk_mul_f32 v[4:5], v[4:5], v[140:141]
	v_pk_mul_f32 v[14:15], v[14:15], v[78:79]
	v_pk_mul_f32 v[10:11], v[10:11], v[130:131]
	v_pk_mul_f32 v[6:7], v[6:7], v[134:135]
	v_pk_mul_f32 v[2:3], v[2:3], v[138:139]
	v_pk_mul_f32 v[64:65], v[64:65], v[80:81]
	v_pk_mul_f32 v[60:61], v[60:61], v[132:133]
	v_pk_mul_f32 v[56:57], v[56:57], v[136:137]
	v_pk_mul_f32 v[52:53], v[52:53], v[140:141]
	v_pk_mul_f32 v[62:63], v[62:63], v[78:79]
	v_pk_mul_f32 v[58:59], v[58:59], v[130:131]
	v_pk_mul_f32 v[54:55], v[54:55], v[134:135]
	v_pk_mul_f32 v[50:51], v[50:51], v[138:139]
	v_pk_mul_f32 v[48:49], v[48:49], v[80:81]
	v_pk_mul_f32 v[44:45], v[44:45], v[132:133]
	v_pk_mul_f32 v[40:41], v[40:41], v[136:137]
	v_pk_mul_f32 v[36:37], v[36:37], v[140:141]
	v_pk_mul_f32 v[46:47], v[46:47], v[78:79]
	v_pk_mul_f32 v[42:43], v[42:43], v[130:131]
	v_pk_mul_f32 v[38:39], v[38:39], v[134:135]
	v_pk_mul_f32 v[34:35], v[34:35], v[138:139]
	v_pk_mul_f32 v[32:33], v[32:33], v[80:81]
	v_pk_mul_f32 v[28:29], v[28:29], v[132:133]
	v_pk_mul_f32 v[24:25], v[24:25], v[136:137]
	v_pk_mul_f32 v[20:21], v[20:21], v[140:141]
	v_pk_mul_f32 v[30:31], v[30:31], v[78:79]
	v_pk_mul_f32 v[26:27], v[26:27], v[130:131]
	v_pk_mul_f32 v[22:23], v[22:23], v[134:135]
	v_pk_mul_f32 v[18:19], v[18:19], v[138:139]
.LBB0_1311:
	s_cmp_ge_u32 s82, s81
	s_waitcnt lgkmcnt(0)
	s_barrier
	s_cbranch_scc1 .LBB0_1313
	v_mov_b32_e32 v177, v207
	s_branch .LBB0_1299
